# plus sample-attention score loop: the 8 f32 K loads of each 16-key block issued together into spare registers, converted behind a counted vmcnt ladder (was one round trip per fragment)
# speedup vs baseline: 1.0057x; 1.0057x over previous
; __device__ __forceinline__ u32x4 pack8(const f32x4 a, const f32x4 b) { u32x4 w; w.x = cvt_pk_bf16(a[0], a[1]); w.y = cvt_pk_bf16(a[2], a[3]); w.z = cvt_pk_bf16(b[0], b[1]); w.w = cvt_pk_bf16(b[2], b[3]); return w; }
; __device__ __forceinline__ bf16x8 ld8f(const float* p) { const f32x4 a = *(const f32x4*)p, b = *(const f32x4*)(p + 4); const u32x4 w = pack8(a, b); return __builtin_bit_cast(bf16x8, w); }
.LBB0_518:
	v_lshl_add_u64 v[90:91], v[68:69], 0, s[78:79]
	v_cmp_ne_u32_e32 vcc, s97, v90
	s_and_saveexec_b64 s[0:1], vcc
	s_xor_b64 s[0:1], exec, s[0:1]
	s_cbranch_execz .LBB0_521
	v_lshl_add_u64 v[92:93], v[84:85], 0, s[78:79]
	global_load_dwordx4 v[96:99], v[92:93], off
	s_waitcnt lgkmcnt(1)
	global_load_dwordx4 v[100:103], v[92:93], off offset:16
	global_load_dwordx4 v[104:107], v[92:93], off offset:128
	global_load_dwordx4 v[108:111], v[92:93], off offset:144
	global_load_dwordx4 v[112:115], v[92:93], off offset:256
	global_load_dwordx4 v[116:119], v[92:93], off offset:272
	global_load_dwordx4 v[120:123], v[92:93], off offset:384
	global_load_dwordx4 v[124:127], v[92:93], off offset:400
	s_waitcnt vmcnt(6)
	v_cvt_pk_bf16_f32 v34, v96, v97
	v_cvt_pk_bf16_f32 v35, v98, v99
	v_cvt_pk_bf16_f32 v36, v100, v101
	v_cvt_pk_bf16_f32 v37, v102, v103
	s_waitcnt vmcnt(4)
	v_cvt_pk_bf16_f32 v38, v104, v105
	v_cvt_pk_bf16_f32 v39, v106, v107
	v_cvt_pk_bf16_f32 v40, v108, v109
	v_cvt_pk_bf16_f32 v41, v110, v111
	s_waitcnt vmcnt(2)
	v_cvt_pk_bf16_f32 v42, v112, v113
	v_cvt_pk_bf16_f32 v43, v114, v115
	v_cvt_pk_bf16_f32 v44, v116, v117
	v_cvt_pk_bf16_f32 v45, v118, v119
	s_waitcnt vmcnt(0)
	v_cvt_pk_bf16_f32 v46, v120, v121
	v_cvt_pk_bf16_f32 v47, v122, v123
	v_cvt_pk_bf16_f32 v48, v124, v125
	v_cvt_pk_bf16_f32 v49, v126, v127
	s_andn2_saveexec_b64 s[0:1], s[0:1]
	s_cbranch_execnz .LBB0_522

; __device__ __forceinline__ u32x4 pack8(const f32x4 a, const f32x4 b) { u32x4 w; w.x = cvt_pk_bf16(a[0], a[1]); w.y = cvt_pk_bf16(a[2], a[3]); w.z = cvt_pk_bf16(b[0], b[1]); w.w = cvt_pk_bf16(b[2], b[3]); return w; }
; __device__ __forceinline__ bf16x8 ld8f(const float* p) { const f32x4 a = *(const f32x4*)p, b = *(const f32x4*)(p + 4); const u32x4 w = pack8(a, b); return __builtin_bit_cast(bf16x8, w); }
.LBB0_523:
	v_cmp_ne_u32_e64 s[0:1], 0, v90
	s_and_saveexec_b64 s[2:3], s[0:1]
	s_xor_b64 s[0:1], exec, s[2:3]
	s_cbranch_execz .LBB0_525
	v_lshl_add_u64 v[90:91], v[86:87], 0, s[78:79]
	global_load_dwordx4 v[128:131], v[90:91], off
	global_load_dwordx4 v[132:135], v[90:91], off offset:16
	global_load_dwordx4 v[136:139], v[90:91], off offset:128
	global_load_dwordx4 v[140:143], v[90:91], off offset:144
	global_load_dwordx4 v[144:147], v[90:91], off offset:256
	global_load_dwordx4 v[148:151], v[90:91], off offset:272
	global_load_dwordx4 v[152:155], v[90:91], off offset:384
	global_load_dwordx4 v[156:159], v[90:91], off offset:400
	s_waitcnt vmcnt(6)
	v_cvt_pk_bf16_f32 v18, v128, v129
	v_cvt_pk_bf16_f32 v19, v130, v131
	v_cvt_pk_bf16_f32 v20, v132, v133
	v_cvt_pk_bf16_f32 v21, v134, v135
	s_waitcnt vmcnt(4)
	v_cvt_pk_bf16_f32 v22, v136, v137
	v_cvt_pk_bf16_f32 v23, v138, v139
	v_cvt_pk_bf16_f32 v24, v140, v141
	v_cvt_pk_bf16_f32 v25, v142, v143
	s_waitcnt vmcnt(2)
	v_cvt_pk_bf16_f32 v26, v144, v145
	v_cvt_pk_bf16_f32 v27, v146, v147
	v_cvt_pk_bf16_f32 v28, v148, v149
	v_cvt_pk_bf16_f32 v29, v150, v151
	s_waitcnt vmcnt(0)
	v_cvt_pk_bf16_f32 v30, v152, v153
	v_cvt_pk_bf16_f32 v31, v154, v155
	v_cvt_pk_bf16_f32 v32, v156, v157
	v_cvt_pk_bf16_f32 v33, v158, v159

; __device__ __forceinline__ u32x4 pack8(const f32x4 a, const f32x4 b) { u32x4 w; w.x = cvt_pk_bf16(a[0], a[1]); w.y = cvt_pk_bf16(a[2], a[3]); w.z = cvt_pk_bf16(b[0], b[1]); w.w = cvt_pk_bf16(b[2], b[3]); return w; }
; __device__ __forceinline__ bf16x8 ld8f(const float* p) { const f32x4 a = *(const f32x4*)p, b = *(const f32x4*)(p + 4); const u32x4 w = pack8(a, b); return __builtin_bit_cast(bf16x8, w); }
.LBB0_641:
	v_lshl_add_u64 v[82:83], v[68:69], 0, s[78:79]
	v_cmp_ne_u32_e32 vcc, s97, v82
	s_and_saveexec_b64 s[0:1], vcc
	s_xor_b64 s[0:1], exec, s[0:1]
	s_cbranch_execz .LBB0_644
	v_lshl_add_u64 v[90:91], v[84:85], 0, s[78:79]
	global_load_dwordx4 v[96:99], v[90:91], off
	global_load_dwordx4 v[100:103], v[90:91], off offset:16
	global_load_dwordx4 v[104:107], v[90:91], off offset:128
	global_load_dwordx4 v[108:111], v[90:91], off offset:144
	global_load_dwordx4 v[112:115], v[90:91], off offset:256
	global_load_dwordx4 v[116:119], v[90:91], off offset:272
	global_load_dwordx4 v[120:123], v[90:91], off offset:384
	global_load_dwordx4 v[124:127], v[90:91], off offset:400
	s_waitcnt vmcnt(6)
	v_cvt_pk_bf16_f32 v34, v96, v97
	v_cvt_pk_bf16_f32 v35, v98, v99
	v_cvt_pk_bf16_f32 v36, v100, v101
	v_cvt_pk_bf16_f32 v37, v102, v103
	s_waitcnt vmcnt(4)
	v_cvt_pk_bf16_f32 v38, v104, v105
	v_cvt_pk_bf16_f32 v39, v106, v107
	v_cvt_pk_bf16_f32 v40, v108, v109
	v_cvt_pk_bf16_f32 v41, v110, v111
	s_waitcnt vmcnt(2)
	v_cvt_pk_bf16_f32 v42, v112, v113
	v_cvt_pk_bf16_f32 v43, v114, v115
	v_cvt_pk_bf16_f32 v44, v116, v117
	v_cvt_pk_bf16_f32 v45, v118, v119
	s_waitcnt vmcnt(0)
	v_cvt_pk_bf16_f32 v46, v120, v121
	v_cvt_pk_bf16_f32 v47, v122, v123
	v_cvt_pk_bf16_f32 v48, v124, v125
	v_cvt_pk_bf16_f32 v49, v126, v127
	s_andn2_saveexec_b64 s[0:1], s[0:1]
	s_cbranch_execnz .LBB0_645

; __device__ __forceinline__ u32x4 pack8(const f32x4 a, const f32x4 b) { u32x4 w; w.x = cvt_pk_bf16(a[0], a[1]); w.y = cvt_pk_bf16(a[2], a[3]); w.z = cvt_pk_bf16(b[0], b[1]); w.w = cvt_pk_bf16(b[2], b[3]); return w; }
; __device__ __forceinline__ bf16x8 ld8f(const float* p) { const f32x4 a = *(const f32x4*)p, b = *(const f32x4*)(p + 4); const u32x4 w = pack8(a, b); return __builtin_bit_cast(bf16x8, w); }
.LBB0_646:
	v_cmp_ne_u32_e64 s[0:1], 0, v82
	s_and_saveexec_b64 s[2:3], s[0:1]
	s_xor_b64 s[0:1], exec, s[2:3]
	s_cbranch_execz .LBB0_648
	v_lshl_add_u64 v[82:83], v[86:87], 0, s[78:79]
	global_load_dwordx4 v[128:131], v[82:83], off
	global_load_dwordx4 v[132:135], v[82:83], off offset:16
	global_load_dwordx4 v[136:139], v[82:83], off offset:128
	global_load_dwordx4 v[140:143], v[82:83], off offset:144
	global_load_dwordx4 v[144:147], v[82:83], off offset:256
	global_load_dwordx4 v[148:151], v[82:83], off offset:272
	global_load_dwordx4 v[152:155], v[82:83], off offset:384
	global_load_dwordx4 v[156:159], v[82:83], off offset:400
	s_waitcnt vmcnt(6)
	v_cvt_pk_bf16_f32 v18, v128, v129
	v_cvt_pk_bf16_f32 v19, v130, v131
	v_cvt_pk_bf16_f32 v20, v132, v133
	v_cvt_pk_bf16_f32 v21, v134, v135
	s_waitcnt vmcnt(4)
	v_cvt_pk_bf16_f32 v22, v136, v137
	v_cvt_pk_bf16_f32 v23, v138, v139
	v_cvt_pk_bf16_f32 v24, v140, v141
	v_cvt_pk_bf16_f32 v25, v142, v143
	s_waitcnt vmcnt(2)
	v_cvt_pk_bf16_f32 v26, v144, v145
	v_cvt_pk_bf16_f32 v27, v146, v147
	v_cvt_pk_bf16_f32 v28, v148, v149
	v_cvt_pk_bf16_f32 v29, v150, v151
	s_waitcnt vmcnt(0)
	v_cvt_pk_bf16_f32 v30, v152, v153
	v_cvt_pk_bf16_f32 v31, v154, v155
	v_cvt_pk_bf16_f32 v32, v156, v157
	v_cvt_pk_bf16_f32 v33, v158, v159
